# v8 + rotary table loop: wave-uniform positions[s] via scalar load (no vmcnt(0) drain of the table stores per iteration)
# speedup vs baseline: 1.0024x; 1.0024x over previous
.LBB0_575:
	v_ashrrev_i32_e32 v6, 7, v5
	s_waitcnt lgkmcnt(0)
	v_readfirstlane_b32 s98, v6
	s_lshl_b32 s98, s98, 2
	s_load_dword s98, s[4:5], s98
	v_add_co_u32_e32 v6, vcc, 0xff800000, v2
	v_add_u32_e32 v5, s20, v5
	s_nop 0
	v_addc_co_u32_e32 v7, vcc, -1, v3, vcc
	v_cmp_lt_i32_e32 vcc, s3, v5
	s_or_b64 s[14:15], vcc, s[14:15]
	s_waitcnt lgkmcnt(0)
	v_cvt_f32_i32_e32 v8, s98
	v_mul_f32_e32 v8, v4, v8
	v_cvt_f64_f32_e32 v[8:9], v8
	v_mul_f64 v[10:11], v[8:9], s[16:17]
	v_rndne_f64_e32 v[10:11], v[10:11]
	v_fma_f64 v[8:9], v[8:9], s[16:17], -v[10:11]
	v_cvt_f32_f64_e32 v8, v[8:9]
	v_cos_f32_e32 v9, v8
	v_sin_f32_e32 v8, v8
	global_store_dword v[6:7], v9, off
	global_store_dword v[2:3], v8, off
	v_lshl_add_u64 v[2:3], v[2:3], 0, s[12:13]
	s_andn2_b64 exec, exec, s[14:15]
	s_cbranch_execnz .LBB0_575

	.amdhsa_kernel _Z10fwd_kernel4Args
		.amdhsa_group_segment_fixed_size 0
		.amdhsa_private_segment_fixed_size 0
		.amdhsa_kernarg_size 440
		.amdhsa_user_sgpr_count 2
		.amdhsa_user_sgpr_dispatch_ptr 0
		.amdhsa_user_sgpr_queue_ptr 0
		.amdhsa_user_sgpr_kernarg_segment_ptr 1
		.amdhsa_user_sgpr_dispatch_id 0
		.amdhsa_user_sgpr_kernarg_preload_length 0
		.amdhsa_user_sgpr_kernarg_preload_offset 0
		.amdhsa_user_sgpr_private_segment_size 0
		.amdhsa_uses_dynamic_stack 0
		.amdhsa_enable_private_segment 0
		.amdhsa_system_sgpr_workgroup_id_x 1
		.amdhsa_system_sgpr_workgroup_id_y 0
		.amdhsa_system_sgpr_workgroup_id_z 0
		.amdhsa_system_sgpr_workgroup_info 0
		.amdhsa_system_vgpr_workitem_id 0
		.amdhsa_next_free_vgpr 256
		.amdhsa_next_free_sgpr 102
		.amdhsa_accum_offset 256
		.amdhsa_reserve_vcc 1
		.amdhsa_float_round_mode_32 0
		.amdhsa_float_round_mode_16_64 0
		.amdhsa_float_denorm_mode_32 3
		.amdhsa_float_denorm_mode_16_64 3
		.amdhsa_dx10_clamp 1
		.amdhsa_ieee_mode 1
		.amdhsa_fp16_overflow 0
		.amdhsa_tg_split 0
		.amdhsa_exception_fp_ieee_invalid_op 0
		.amdhsa_exception_fp_denorm_src 0
		.amdhsa_exception_fp_ieee_div_zero 0
		.amdhsa_exception_fp_ieee_overflow 0
		.amdhsa_exception_fp_ieee_underflow 0
		.amdhsa_exception_fp_ieee_inexact 0
		.amdhsa_exception_int_div_zero 0
	.end_amdhsa_kernel

amdhsa.kernels:
  - .agpr_count:     0
    .args:
      - .offset:         0
        .size:           184
        .value_kind:     by_value
      - .offset:         184
        .size:           4
        .value_kind:     hidden_block_count_x
      - .offset:         188
        .size:           4
        .value_kind:     hidden_block_count_y
      - .offset:         192
        .size:           4
        .value_kind:     hidden_block_count_z
      - .offset:         196
        .size:           2
        .value_kind:     hidden_group_size_x
      - .offset:         198
        .size:           2
        .value_kind:     hidden_group_size_y
      - .offset:         200
        .size:           2
        .value_kind:     hidden_group_size_z
      - .offset:         202
        .size:           2
        .value_kind:     hidden_remainder_x
      - .offset:         204
        .size:           2
        .value_kind:     hidden_remainder_y
      - .offset:         206
        .size:           2
        .value_kind:     hidden_remainder_z
      - .offset:         224
        .size:           8
        .value_kind:     hidden_global_offset_x
      - .offset:         232
        .size:           8
        .value_kind:     hidden_global_offset_y
      - .offset:         240
        .size:           8
        .value_kind:     hidden_global_offset_z
      - .offset:         248
        .size:           2
        .value_kind:     hidden_grid_dims
      - .offset:         304
        .size:           4
        .value_kind:     hidden_dynamic_lds_size
    .group_segment_fixed_size: 0
    .kernarg_segment_align: 8
    .kernarg_segment_size: 440
    .language:       OpenCL C
    .language_version:
      - 2
      - 0
    .max_flat_workgroup_size: 512
    .name:           _Z10fwd_kernel4Args
    .private_segment_fixed_size: 0
    .sgpr_count:     108
    .sgpr_spill_count: 3
    .symbol:         _Z10fwd_kernel4Args.kd
    .uniform_work_group_size: 1
    .uses_dynamic_stack: false
    .vgpr_count:     256
    .vgpr_spill_count: 0
    .wavefront_size: 64
